# P2 swap + same for P4 (half the workgroups run combine before ssd_out)
# speedup vs baseline: 1.0297x; 1.0075x over previous
.LBB0_932:
	s_cmp_lt_i32 s86, 5
	s_cselect_b64 s[0:1], -1, 0
	s_cmp_gt_i32 s87, 4
	s_cselect_b64 s[2:3], -1, 0
	s_and_b64 s[0:1], s[0:1], s[2:3]
	s_andn2_b64 vcc, exec, s[0:1]
	s_cbranch_vccnz .LBB0_1057
	s_mov_b32 s70, 2
	s_bitcmp1_b32 s33, 3
	s_cbranch_scc0 .Lmy_p4_pre
	s_mov_b32 s70, 0
.Lmy_p4_pre:
	s_cmp_eq_u32 s70, 0
	s_cbranch_scc0 .Lmy_p4_ssd
	v_lshrrev_b32_e32 v0, 6, v158
	v_and_b32_e32 v97, 63, v158
	s_branch .LBB0_1000
.Lmy_p4_ssd:
	s_cmpk_lt_i32 s33, 0x100
	s_cbranch_scc1 .LBB0_935
	v_lshrrev_b32_e32 v0, 6, v158
	s_waitcnt vmcnt(4)
	v_and_b32_e32 v97, 63, v158
	s_cbranch_execz .LBB0_936
	s_branch .LBB0_1000

.LBB0_1000:
	s_cmp_eq_u32 s70, 1
	s_cbranch_scc1 .Lmy_p4_done
	v_lshl_add_u32 v4, s33, 3, v0
	s_movk_i32 s0, 0x2000
	v_cmp_gt_i32_e32 vcc, s0, v4
	s_and_saveexec_b64 s[2:3], vcc
	s_cbranch_execz .LBB0_1003
	v_mbcnt_lo_u32_b32 v0, -1, 0
	v_mbcnt_hi_u32_b32 v0, -1, v0
	v_and_b32_e32 v1, 64, v0
	v_add_u32_e32 v1, 64, v1
	v_xor_b32_e32 v2, 1, v0
	v_cmp_lt_i32_e32 vcc, v2, v1
	s_lshl_b32 s4, s88, 3
	v_ashrrev_i32_e32 v5, 31, v4
	v_cndmask_b32_e32 v2, v0, v2, vcc
	v_lshlrev_b32_e32 v18, 2, v2
	v_xor_b32_e32 v2, 2, v0
	v_cmp_lt_i32_e32 vcc, v2, v1
	s_movk_i32 s0, 0x3000
	v_mad_i64_i32 v[8:9], s[0:1], v4, s0, 0
	v_cndmask_b32_e32 v2, v0, v2, vcc
	v_lshlrev_b32_e32 v19, 2, v2
	v_xor_b32_e32 v2, 4, v0
	v_cmp_lt_i32_e32 vcc, v2, v1
	s_ashr_i32 s5, s4, 31
	s_waitcnt lgkmcnt(0)
	v_lshlrev_b64 v[10:11], 11, v[4:5]
	v_cndmask_b32_e32 v2, v0, v2, vcc
	v_lshlrev_b32_e32 v20, 2, v2
	v_xor_b32_e32 v2, 8, v0
	v_cmp_lt_i32_e32 vcc, v2, v1
	v_lshlrev_b64 v[12:13], 6, v[4:5]
	s_mul_i32 s6, s88, 0x18000
	v_cndmask_b32_e32 v2, v0, v2, vcc
	v_lshlrev_b32_e32 v21, 2, v2
	v_xor_b32_e32 v2, 16, v0
	v_cmp_lt_i32_e32 vcc, v2, v1
	s_mul_hi_i32 s7, s4, 0x3000
	s_lshl_b64 s[8:9], s[4:5], 11
	v_cndmask_b32_e32 v2, v0, v2, vcc
	v_lshlrev_b32_e32 v22, 2, v2
	v_xor_b32_e32 v2, 32, v0
	v_cmp_lt_i32_e32 vcc, v2, v1
	v_mov_b32_e32 v1, 0
	v_and_or_b32 v12, v158, 60, v12
	v_cndmask_b32_e32 v0, v0, v2, vcc
	v_lshlrev_b32_e32 v23, 2, v0
	v_lshlrev_b32_e32 v0, 6, v97
	v_lshl_add_u64 v[6:7], s[62:63], 0, v[0:1]
	v_lshlrev_b32_e32 v0, 5, v97
	v_or_b32_e32 v8, v8, v0
	v_or_b32_e32 v10, v10, v0
	s_lshl_b64 s[10:11], s[4:5], 6
	s_mov_b64 s[12:13], 0
	s_mov_b64 s[14:15], 0x5c00000
	s_mov_b32 s5, 0x5c00000
	s_mov_b64 s[16:17], 0x6c00000
	s_mov_b32 s20, 0x6c00000
	s_mov_b64 s[18:19], 0x7c00000
	s_mov_b32 s21, 0x7c00000
	v_mov_b32_e32 v5, 0x358637bd
	s_mov_b32 s22, 0x800000
	s_mov_b32 s23, 0x9400000
	s_movk_i32 s24, 0x1fff

.LBB0_1003:
	s_or_b64 exec, exec, s[2:3]
	s_cmp_eq_u32 s70, 0
	s_cbranch_scc0 .Lmy_p4_done
	s_mov_b32 s70, 1
	s_waitcnt vmcnt(0) lgkmcnt(0)
	s_branch .Lmy_p4_pre
.Lmy_p4_done:
	s_cmp_lt_i32 s87, 6
	s_cbranch_scc1 .LBB0_1057
	s_waitcnt vmcnt(0)
	s_waitcnt lgkmcnt(0)
	s_barrier
	s_mov_b64 s[0:1], exec
	v_readlane_b32 s2, v252, 5
	v_readlane_b32 s3, v252, 6
	s_and_b64 s[2:3], s[0:1], s[2:3]
	s_mov_b64 exec, s[2:3]
	s_cbranch_execz .LBB0_1056
	s_add_i32 s2, 0, 0x25fc0
	v_mov_b32_e32 v0, s2
	s_waitcnt vmcnt(0) expcnt(0) lgkmcnt(0)
	ds_read_b32 v2, v0
	s_add_i32 s2, 0, 0x25fc4
	v_mov_b32_e32 v0, s2
	ds_read_b32 v0, v0
	s_waitcnt lgkmcnt(1)
	v_cmp_ne_u32_e32 vcc, 0, v2
	s_cbranch_vccnz .LBB0_1020
	v_readlane_b32 s2, v252, 0
	v_readlane_b32 s3, v252, 1
	s_load_dwordx2 s[6:7], s[2:3], 0x4
	s_add_u32 s2, s84, 0x5900200
	s_addc_u32 s3, s85, 0
	s_add_u32 s4, s84, 0x5900400
	s_addc_u32 s5, s85, 0
	s_waitcnt lgkmcnt(0)
	s_mul_i32 s44, s6, s88
	s_add_u32 s6, s84, 0x5900500
	s_mul_i32 s44, s44, s7
	s_addc_u32 s7, s85, 0
	s_add_u32 s8, s84, 0x5900600
	s_addc_u32 s9, s85, 0
	s_add_u32 s10, s84, 0x5900700
	s_addc_u32 s11, s85, 0
	s_add_u32 s12, s84, 0x5900800
	s_addc_u32 s13, s85, 0
	s_add_u32 s14, s84, 0x5900900
	s_addc_u32 s15, s85, 0
	s_add_u32 s16, s84, 0x5900a00
	s_addc_u32 s17, s85, 0
	s_add_u32 s18, s84, 0x5900b00
	s_addc_u32 s19, s85, 0
	s_add_u32 s20, s84, 0x5900c00
	s_addc_u32 s21, s85, 0
	s_add_u32 s22, s84, 0x5900d00
	s_addc_u32 s23, s85, 0
	s_add_u32 s24, s84, 0x5900e00
	s_addc_u32 s25, s85, 0
	s_add_u32 s26, s84, 0x5900f00
	s_addc_u32 s27, s85, 0
	s_add_u32 s28, s84, 0x5901000
	s_addc_u32 s29, s85, 0
	s_add_u32 s30, s84, 0x5901100
	s_addc_u32 s31, s85, 0
	s_add_u32 s34, s84, 0x5901200
	s_addc_u32 s35, s85, 0
	s_add_u32 s36, s84, 0x5901300
	s_addc_u32 s37, s85, 0
	s_mov_b32 s45, 1
	v_mov_b32_e32 v16, 0
	s_branch .LBB0_1008
